# prompt SSD chains: the 8 heads sharing a (sequence, B/C group) pair run on workgroups of one XCD (item index permuted from bx) so the shared B / B^T / C tile loads hit that XCD's L2
# speedup vs baseline: 1.0184x; 1.0046x over previous
; __global__ void __launch_bounds__(512, 2) mk_fwd(Args args) {
;     ...
;         const int npb = (G >= 256) ? 128 : (G / 2 > 0 ? G / 2 : 1);
;         if (bx < npb) { if (psel != 2) for (int it = bx; it < NB * NH; it += npb) ssd_prompt(lds, it >> 5, it & 31, XBC, CS, XT1, XT2, BT, MIX, out + O_PSSM); }
.LBB0_440:
	s_and_b64 vcc, exec, s[4:5]
	s_cbranch_vccz .LBB0_490
	v_readlane_b32 s0, v253, 6
	s_cmp_eq_u32 s0, 2
	s_cbranch_scc1 .LBB0_490
	v_writelane_b32 v253, s96, 21
	s_mov_b64 s[92:93], 0x80000
	v_mov_b32_e32 v97, 0
	v_writelane_b32 v253, s97, 22
	s_mov_b32 s97, 0
	v_readlane_b32 s4, v253, 16
	v_readlane_b32 s6, v253, 18
	v_readlane_b32 s7, v253, 19
	s_add_u32 s0, s6, 0x7580000
	s_addc_u32 s1, s7, 0
	v_readlane_b32 s5, v253, 17
	v_writelane_b32 v253, s0, 23
	s_movk_i32 s33, 0x1800
	s_mov_b64 s[72:73], 0x20000
	v_writelane_b32 v253, s1, 24
	s_add_u32 s0, s4, 0x2000000
	s_addc_u32 s1, s5, 0
	v_writelane_b32 v253, s0, 25
	s_mov_b32 s8, s2
	s_nop 0
	v_writelane_b32 v253, s1, 26
	s_add_u32 s0, s4, 0x2800000
	v_writelane_b32 v253, s0, 27
	s_addc_u32 s0, s5, 0
	v_writelane_b32 v253, s0, 28
	s_add_u32 s0, s6, 0x135d0000
	s_addc_u32 s1, s7, 0
	s_add_u32 s3, s6, 0x1acd0000
	v_writelane_b32 v253, s3, 29
	s_addc_u32 s3, s7, 0
	v_writelane_b32 v253, s3, 30
	s_add_u32 s3, s4, 0x4400000
	v_writelane_b32 v253, s3, 31
	s_addc_u32 s3, s5, 0
	s_add_u32 s6, s6, 0x7600000
	v_writelane_b32 v253, s3, 32
	s_addc_u32 s7, s7, 0
	v_writelane_b32 v253, s6, 33
	s_nop 1
	v_writelane_b32 v253, s7, 34
	s_add_u32 s6, s4, 0x80000
	s_addc_u32 s7, s5, 0
	v_writelane_b32 v253, s6, 35
	s_add_u32 s3, s4, 0x2020000
	s_nop 0
	v_writelane_b32 v253, s7, 36
	v_writelane_b32 v253, s3, 37
	s_addc_u32 s3, s5, 0
	v_writelane_b32 v253, s3, 38
	s_add_i32 s3, 0, 0x19800
	v_writelane_b32 v253, s3, 39
	s_add_i32 s3, 0, 0x1dc00
	v_writelane_b32 v253, s3, 40
	v_writelane_b32 v253, s0, 41
	s_mov_b32 s6, s2
	s_nop 0
	v_writelane_b32 v253, s1, 42
	v_mov_b64_e32 v[98:99], s[0:1]
	s_add_i32 s0, 0, 0x11000
	v_writelane_b32 v253, s0, 43
	s_add_i32 s0, 0, 0x15400
	v_writelane_b32 v253, s0, 44
	v_writelane_b32 v253, s2, 45
	s_and_b32 s0, s2, 7
	s_lshl_b32 s0, s0, 1
	s_lshr_b32 s1, s2, 6
	s_add_u32 s0, s0, s1
	s_lshl_b32 s0, s0, 3
	s_bfe_u32 s1, s2, 0x30003
	s_add_u32 s8, s0, s1
	s_mov_b32 s6, s8
	s_branch .LBB0_444
